# seam 3 (compress stage 2 -> attention) group-local too: phase 3 items re-mapped per group, Wout checks a phase-3 completion counter before overwriting the split-K partials
# speedup vs baseline: 1.0227x; 1.0037x over previous
; #define LAS __attribute__((address_space(3)))
; __device__ __forceinline__ void phase3(const Args& a, LAS unsigned char* lds) {
;     const int tid = threadIdx.x, lane = tid & 63, wave = tid >> 6;
;     unsigned char* ws = a.ws;
;     const float* part = (const float*)(ws + WS_PART); const float* c1p = (const float*)(ws + WS_C1P);
;     bf16_t* kcmp = (bf16_t*)(ws + WS_KCMP); bf16_t* vcmpT = (bf16_t*)(ws + WS_VCMPT);
;     LAS float* w2s = (LAS float*)lds;
;     LAS float* c1s = w2s + 256 * 64;
;     LAS float* hids = c1s + 256;
;     const int nchunk = 8192 / 32;
;     for (int item = blockIdx.x; item < nchunk; item += gridDim.x) {
;         const int kv = (item * 32) >> 12;
;         __syncthreads();
;         { const f32x4* src = (const f32x4*)(a.in[7] + (size_t)kv * 256 * 64);
; #pragma unroll
;           for (int i = 0; i < 8; ++i) ((LAS f32x4*)w2s)[tid + 512 * i] = src[tid + 512 * i]; }
;         if (tid < 256) { float t = 0.f;
; #pragma unroll
;             for (int kch = 0; kch < 64; ++kch) t += c1p[kch * 512 + kv * 256 + tid];
;             c1s[tid] = t; }
;         __syncthreads();
; #pragma unroll 1
;         for (int rr = 0; rr < 4; ++rr) {
;             const int R = item * 32 + wave * 4 + rr, bh = (R >> 7) & 31, n = R & 127;
.LBB0_585:
	v_readlane_b32 s0, v254, 0
	v_readlane_b32 s1, v254, 1
	s_cmp_lt_i32 s0, 4
	s_cselect_b64 s[0:1], -1, 0
	s_and_b64 s[8:9], s[0:1], s[72:73]
	s_andn2_b64 vcc, exec, s[8:9]
	s_cbranch_vccnz .LBB0_680
	s_cmpk_gt_i32 s70, 0xff
	s_cbranch_scc1 .LBB0_599
	s_add_u32 s10, s78, 0x1a90000
	s_movk_i32 s0, 0x100
	s_addc_u32 s11, s79, 0
	v_cmp_gt_u32_e64 s[2:3], s0, v184
	s_add_i32 s0, 0, 0x10000
	v_lshlrev_b32_e32 v2, 4, v151
	v_mov_b32_e32 v3, 0
	v_lshl_add_u32 v12, v184, 2, s0
	v_add_u32_e32 v14, s0, v2
	v_lshl_add_u64 v[4:5], s[78:79], 0, v[2:3]
	s_mov_b64 s[0:1], 0x2600000
	v_lshl_add_u64 v[4:5], v[4:5], 0, s[0:1]
	v_lshlrev_b32_e32 v15, 10, v149
	s_add_i32 s0, 0, 0x10400
	v_lshlrev_b32_e32 v0, 2, v151
	v_mov_b32_e32 v1, v3
	v_add3_u32 v16, s0, v15, v2
	v_or_b32_e32 v2, 0x400, v184
	v_or_b32_e32 v10, 0x800, v184
	v_or_b32_e32 v20, 0xc00, v184
	v_lshl_add_u64 v[6:7], s[80:81], 0, v[0:1]
	v_lshlrev_b32_e32 v1, 4, v2
	v_mbcnt_lo_u32_b32 v2, -1, 0
	v_lshlrev_b32_e32 v13, 2, v149
	v_lshlrev_b32_e32 v17, 7, v151
	v_lshl_add_u32 v18, v184, 4, 0
	v_lshlrev_b32_e32 v8, 4, v184
	v_mov_b32_e32 v9, v3
	s_movk_i32 s14, 0x2000
	s_movk_i32 s15, 0x6000
	v_lshlrev_b32_e32 v19, 4, v10
	v_lshlrev_b32_e32 v20, 4, v20
	s_movk_i32 s16, 0x7f
	s_mov_b32 s17, 0x3e000
	s_mov_b32 s18, 0x800000
	s_movk_i32 s19, 0x7fff
	v_mov_b32_e32 v21, 0x358637bd
	v_mbcnt_hi_u32_b32 v22, -1, v2
	s_mov_b32 s20, s70
	s_cmp_lg_u32 s88, 0x100
	s_cbranch_scc1 .Lp3_nomap
	s_and_b32 s0, s70, 7
	s_lshl_b32 s0, s0, 1
	s_lshr_b32 s1, s70, 7
	s_add_i32 s0, s0, s1
	s_lshl_b32 s0, s0, 3
	s_bfe_u32 s1, s70, 0x10006
	s_lshl_b32 s1, s1, 7
	s_bfe_u32 s20, s70, 0x30003
	s_or_b32 s20, s20, s0
	s_or_b32 s20, s20, s1
.Lp3_nomap:
	s_branch .LBB0_589
.LBB0_588:
	s_add_i32 s20, s20, s88
	s_cmpk_gt_i32 s20, 0xff
	s_cbranch_scc1 .LBB0_599

; #define LAS __attribute__((address_space(3)))
; __device__ __forceinline__ unsigned xb_ld(unsigned* p) { return __hip_atomic_load(p, __ATOMIC_RELAXED, __HIP_MEMORY_SCOPE_AGENT); }
; __device__ __forceinline__ unsigned xb_add(unsigned* p, unsigned v) { return __hip_atomic_fetch_add(p, v, __ATOMIC_RELAXED, __HIP_MEMORY_SCOPE_AGENT); }
; __device__ __forceinline__ unsigned xb_xcc_id() { return (unsigned)__builtin_amdgcn_s_getreg((3 << 11) | 20) & 0xFu; }
; __device__ __forceinline__ void grid_barrier(unsigned* barw, int k, volatile LAS unsigned* st) {
;     asm volatile("s_waitcnt vmcnt(0)" ::: "memory");
;     __syncthreads();
;     if (threadIdx.x == 0) {
;         __builtin_amdgcn_s_waitcnt(0);
;         const unsigned x = xb_xcc_id();
;         unsigned nloc = st[0], nx = st[1];
;         if (nloc == 0u) {
;             const unsigned G = gridDim.x;
;             for (;;) { unsigned sum = 0u, cnt = 0u, mine = 0u;
; #pragma unroll
;                 for (unsigned j = 0; j < 16; ++j) { const unsigned c = xb_ld(barw + 64 * j); sum += c; cnt += (c > 0u) ? 1u : 0u; mine = (j == x) ? c : mine; }
;                 if (sum == G) { nloc = mine; nx = cnt; break; }
;                 __builtin_amdgcn_s_sleep(1); }
;             st[0] = nloc; st[1] = nx;
;         }
;         unsigned* sb = barw + 1024 + k * 2304;
;         const unsigned old = xb_add(sb + 64 * x, 1u);
;         if (old + 1u == nloc) {
;             __builtin_amdgcn_fence(__ATOMIC_RELEASE, "agent");
;             asm volatile("s_waitcnt vmcnt(0)" ::: "memory");
;             const unsigned og = xb_add(sb + 2048, 1u);
;             if (og + 1u == nx) xb_add(sb + 2112, 1u);
;             else while (xb_ld(sb + 2112) == 0u) __builtin_amdgcn_s_sleep(1);
;             __builtin_amdgcn_fence(__ATOMIC_ACQUIRE, "agent");
;             xb_add(sb + 1024 + 64 * x, 1u);
;             asm volatile("s_waitcnt vmcnt(0)" ::: "memory");
;         } else {
;             while (xb_ld(sb + 1024 + 64 * x) == 0u) __builtin_amdgcn_s_sleep(1);
;             __builtin_amdgcn_fence(__ATOMIC_ACQUIRE, "agent");
;             asm volatile("s_waitcnt vmcnt(0)" ::: "memory");
;         }
;     }
;     __syncthreads();
; }
.LBB0_680:
	v_readlane_b32 s0, v254, 0
	v_readlane_b32 s1, v254, 1
	s_cmp_gt_i32 s1, 4
	s_cselect_b64 s[72:73], -1, 0
	s_and_b64 s[0:1], s[8:9], s[72:73]
	s_andn2_b64 vcc, exec, s[0:1]
	s_cbranch_vccnz .LBB0_709
	s_waitcnt vmcnt(0)
	s_waitcnt vmcnt(0) lgkmcnt(0)
	s_barrier
	s_mov_b64 s[74:75], exec
	v_readlane_b32 s0, v254, 2
	v_readlane_b32 s1, v254, 3
	s_and_b64 s[0:1], s[74:75], s[0:1]
	s_mov_b64 exec, s[0:1]
	s_cbranch_execz .LBB0_708
	s_add_u32 s4, s78, 0x12f40
	s_addc_u32 s5, s79, 0
	v_mov_b32_e32 v0, 0
	v_mov_b32_e32 v1, 1
	global_atomic_add v0, v1, s[4:5]
	s_cmp_lg_u32 s88, 0x100
	s_cbranch_scc1 .Lgb3_orig
	s_waitcnt vmcnt(0) lgkmcnt(0)
	s_and_b32 s0, s70, 7
	s_lshl_b32 s0, s0, 8
	s_add_i32 s0, s0, 0x12400
	s_add_u32 s4, s78, s0
	s_addc_u32 s5, s79, 0
	s_lshr_b32 s6, s88, 3
	s_getreg_b32 s8, hwreg(HW_REG_XCC_ID, 0, 4)
	s_lshl_b32 s8, 1, s8
	v_mov_b32_e32 v0, 0
	v_mov_b32_e32 v1, s8
	global_atomic_or v2, v0, v1, s[4:5] offset:64 sc0
	s_waitcnt vmcnt(0)
	v_mov_b32_e32 v1, 1
	global_atomic_add v2, v0, v1, s[4:5] sc0
	s_waitcnt vmcnt(0)
	v_readfirstlane_b32 s7, v2
	s_add_i32 s7, s7, 1
	s_cmp_ge_u32 s7, s6
	s_cbranch_scc1 .Lgb3_all1

; #define LAS __attribute__((address_space(3)))
;     __device__ bool next(int i, Unit& u) const { const long L = (long)i * G + c; if (L >= 128) return false; u.pm = (int)L & 31; u.pn = u.pm >> 4; u.koff = ((int)L >> 5) * 1024; return true; }
;     __host__ __device__ bool next(int i, Unit& u) const {
;         const long L = (long)i * G + c; if (L >= nwg) return false;
;         int wgid = (int)L; { const int q = nwg / NXCD, r = nwg % NXCD, xcd = wgid % NXCD, off = wgid / NXCD; wgid = (xcd < r ? xcd * (q + 1) : r * (q + 1) + (xcd - r) * q) + off; }
;         const int nig = WGM * nN, gid = wgid / nig, fm = gid * WGM, gsz = (nM - fm) < WGM ? (nM - fm) : WGM;
;         u.pm = fm + ((wgid % nig) % gsz); u.pn = (wgid % nig) / gsz; u.koff = 0; return true;
; __global__ void __launch_bounds__(NWAVES * 64, 2) fwd_kernel(Args args) {
;     ...
;     if (IN(5)) {
;         pg8::Gemm g{(const bf16_t*)(ws + WS_O), (const bf16_t*)(ws + WS_WOUT), T, DM, DM, DM, DM};
;         pg8::StaticOrder So; So.init(T, DM, G, (int)blockIdx.x);
;         EpiWout E{(const bf16_t*)(ws + WS_XB), (bf16_t*)(ws + WS_X2B), (float*)(ws + WS_SSQP), (LAS float*)(lds + 131072)};
;         pg8::gemm_phase<EpiWout, pg8::StaticOrder, true, true>(lds, g, So, E);
.LBB0_915:
	s_mov_b32 s98, 0
	s_add_u32 s100, s78, 0x12f40
	s_addc_u32 s101, s79, 0
	v_readlane_b32 s0, v254, 0
	v_readlane_b32 s1, v254, 1
	s_cmp_lt_i32 s0, 6
	s_cselect_b64 s[0:1], -1, 0
	s_and_b64 s[0:1], s[0:1], s[72:73]
	s_andn2_b64 vcc, exec, s[0:1]
	s_cbranch_vccnz .LBB0_960
	s_cmpk_lt_i32 s70, 0x200
	s_cselect_b64 s[2:3], -1, 0
	s_cmpk_gt_i32 s70, 0x1ff
	v_readfirstlane_b32 s6, v184
	s_cbranch_scc1 .LBB0_922
	s_ashr_i32 s4, s70, 31
	s_lshr_b32 s4, s4, 29
	s_add_i32 s9, s70, s4
	s_and_b32 s4, s9, -8
	s_sub_i32 s7, s70, s4
	s_cmp_gt_i32 s7, -1
	s_cbranch_scc0 .LBB0_919
	s_lshl_b32 s8, s7, 6
	s_ashr_i32 s4, s9, 3
	s_cbranch_execz .LBB0_920
	s_branch .LBB0_921

; #define PG8_STAGE(bufoff, gbase, voff) do { _Pragma("unroll") for (int _i = 0; _i < 2; ++_i) \
;         __builtin_amdgcn_global_load_lds((const unsigned*)((const char*)(gbase) + (voff)[_i]), (PG8_LAS unsigned*)(lds + (bufoff) + ldsw + _i * 8192), 16, 0, 0); } while (0)
; #define PG8_LDA(dst, b, h) do { _Pragma("unroll") for (int m = 0; m < 4; ++m) _Pragma("unroll") for (int k = 0; k < 2; ++k) dst[m][k] = *(const PG8_LAS bf16x8*)(lds + PG8_SA(b, h) + aoff + m * 2048 + k * 1024); } while (0)
; #define PG8_LDB(dst, b, h) do { _Pragma("unroll") for (int n = 0; n < 2; ++n) _Pragma("unroll") for (int k = 0; k < 2; ++k) dst[n][k] = *(const PG8_LAS bf16x8*)(lds + PG8_SB(b, h) + boff + n * 2048 + k * 1024); } while (0)
; #define PG8_MMA(ai, bj, At, Bt) do { __builtin_amdgcn_s_setprio(1); _Pragma("unroll") for (int m = 0; m < 4; ++m) _Pragma("unroll") for (int n = 0; n < 2; ++n) _Pragma("unroll") for (int k = 0; k < 2; ++k) \
;         acc[ai][bj][m][n] = __builtin_amdgcn_mfma_f32_16x16x32_bf16(Bt[n][k], At[m][k], acc[ai][bj][m][n], 0, 0, 0); __builtin_amdgcn_s_setprio(0); } while (0)
; #define PG8_WAIT_V(n) asm volatile("s_waitcnt vmcnt(" #n ")" ::: "memory")
; template <class Epi, class Sched, bool ALIGN_EPI = false, bool SP2 = false>
; __device__ __forceinline__ void gemm_phase(PG8_LAS unsigned char* lds, const Gemm g, const Sched& S, const Epi& E) {
;     ...
;             PG8_LDB(B0, 0, 0); PG8_LDB(B1, 0, 1); PG8_SCHED; PG8_LDA(At, 0, 0); PG8_STAGE(PG8_SA(1, 1), a1 + hstepA, voffA);
;             PG8_WAIT_V(8); PG8_WAIT_L(0); PG8_BAR; PG8_MMA(0, 0, At, B0); PG8_MMA(0, 1, At, B1); PG8_BAR; PG8_SCHED;
;             PG8_LDA(At, 0, 1); PG8_STAGE(PG8_SB(0, 0), b2, voffB); PG8_STAGE(PG8_SB(0, 1), b2 + hstepB, voffB); PG8_STAGE(PG8_SA(0, 0), a2, voffA);
;             PG8_WAIT_V(8); PG8_WAIT_L(0); PG8_BAR; PG8_MMA(1, 0, At, B0); PG8_MMA(1, 1, At, B1); PG8_BAR; PG8_SCHED;
;             PG8_LDB(B0, 1, 0); PG8_LDB(B1, 1, 1); PG8_SCHED; PG8_LDA(At, 1, 0); PG8_STAGE(PG8_SA(0, 1), a2 + hstepA, voffA);
;             PG8_WAIT_V(8); PG8_WAIT_L(0); PG8_BAR; PG8_MMA(0, 0, At, B0); PG8_MMA(0, 1, At, B1); PG8_BAR; PG8_SCHED;
;             PG8_LDA(At, 1, 1); PG8_STAGE(PG8_SB(1, 0), b3, voffB); PG8_STAGE(PG8_SB(1, 1), b3 + hstepB, voffB); PG8_STAGE(PG8_SA(1, 0), a3, voffA);
;             PG8_WAIT_V(8); PG8_WAIT_L(0); PG8_BAR; PG8_MMA(1, 0, At, B0); PG8_MMA(1, 1, At, B1); PG8_BAR; PG8_SCHED;
.LBB0_935:
	ds_read_b128 v[120:123], v237
	ds_read_b128 v[124:127], v237 offset:1024
	ds_read_b128 v[136:139], v237 offset:2048
	ds_read_b128 v[140:143], v237 offset:3072
	ds_read_b128 v[144:147], v238
	ds_read_b128 v[148:151], v238 offset:1024
	ds_read_b128 v[152:155], v238 offset:2048
	ds_read_b128 v[156:159], v238 offset:3072
	s_add_u32 s38, s36, 0xfffc0080
	s_addc_u32 s39, s37, -1
	s_cmp_eq_u32 s58, 12
	s_cselect_b32 s41, s9, s39
	s_cselect_b32 s40, s27, s38
	s_cselect_b32 s39, s25, s57
	s_cselect_b32 s38, s35, s56
	v_lshl_add_u64 v[214:215], s[36:37], 0, v[198:199]
	s_add_i32 m0, s44, 0xc000
	ds_read_b128 v[160:163], v239
	ds_read_b128 v[164:167], v239 offset:1024
	ds_read_b128 v[168:171], v239 offset:2048
	ds_read_b128 v[172:175], v239 offset:3072
	ds_read_b128 v[176:179], v239 offset:4096
	ds_read_b128 v[180:183], v239 offset:5120
	ds_read_b128 v[206:209], v239 offset:6144
	ds_read_b128 v[210:213], v239 offset:7168
	global_load_lds_dwordx4 v[214:215], off
	v_lshl_add_u64 v[214:215], s[36:37], 0, v[200:201]
	s_add_i32 m0, s44, 0xe000
	s_nop 0
	global_load_lds_dwordx4 v[214:215], off
	s_waitcnt vmcnt(8)
	s_waitcnt lgkmcnt(0)
	s_barrier
	s_setprio 1
	s_waitcnt lgkmcnt(0)
	v_mfma_f32_16x16x32_bf16 v[132:135], v[120:123], v[160:163], v[132:135]
	v_mfma_f32_16x16x32_bf16 v[128:131], v[136:139], v[160:163], v[128:131]
	v_mfma_f32_16x16x32_bf16 v[108:111], v[120:123], v[168:171], v[108:111]
	v_mfma_f32_16x16x32_bf16 v[104:107], v[136:139], v[168:171], v[104:107]
	v_mfma_f32_16x16x32_bf16 v[92:95], v[120:123], v[176:179], v[92:95]
	v_mfma_f32_16x16x32_bf16 v[88:91], v[136:139], v[176:179], v[88:91]
	v_mfma_f32_16x16x32_bf16 v[76:79], v[120:123], v[206:209], v[76:79]
	v_mfma_f32_16x16x32_bf16 v[72:75], v[136:139], v[206:209], v[72:75]
	v_mfma_f32_16x16x32_bf16 v[132:135], v[124:127], v[164:167], v[132:135]
	v_mfma_f32_16x16x32_bf16 v[128:131], v[140:143], v[164:167], v[128:131]
	v_mfma_f32_16x16x32_bf16 v[108:111], v[124:127], v[172:175], v[108:111]
	v_mfma_f32_16x16x32_bf16 v[104:107], v[140:143], v[172:175], v[104:107]
	v_mfma_f32_16x16x32_bf16 v[92:95], v[124:127], v[180:183], v[92:95]
	v_mfma_f32_16x16x32_bf16 v[88:91], v[140:143], v[180:183], v[88:91]
	v_mfma_f32_16x16x32_bf16 v[76:79], v[124:127], v[210:213], v[76:79]
	v_mfma_f32_16x16x32_bf16 v[72:75], v[140:143], v[210:213], v[72:75]
	s_setprio 0
	s_setprio 1
	v_mfma_f32_16x16x32_bf16 v[116:119], v[144:147], v[160:163], v[116:119]
	v_mfma_f32_16x16x32_bf16 v[112:115], v[152:155], v[160:163], v[112:115]
	v_mfma_f32_16x16x32_bf16 v[100:103], v[144:147], v[168:171], v[100:103]
	v_mfma_f32_16x16x32_bf16 v[96:99], v[152:155], v[168:171], v[96:99]
	v_mfma_f32_16x16x32_bf16 v[84:87], v[144:147], v[176:179], v[84:87]
	v_mfma_f32_16x16x32_bf16 v[80:83], v[152:155], v[176:179], v[80:83]
	v_mfma_f32_16x16x32_bf16 v[68:71], v[144:147], v[206:209], v[68:71]
	v_mfma_f32_16x16x32_bf16 v[64:67], v[152:155], v[206:209], v[64:67]
	v_mfma_f32_16x16x32_bf16 v[116:119], v[148:151], v[164:167], v[116:119]
	v_mfma_f32_16x16x32_bf16 v[112:115], v[156:159], v[164:167], v[112:115]
	v_mfma_f32_16x16x32_bf16 v[100:103], v[148:151], v[172:175], v[100:103]
	v_mfma_f32_16x16x32_bf16 v[96:99], v[156:159], v[172:175], v[96:99]
	v_mfma_f32_16x16x32_bf16 v[84:87], v[148:151], v[180:183], v[84:87]
	v_mfma_f32_16x16x32_bf16 v[80:83], v[156:159], v[180:183], v[80:83]
	v_mfma_f32_16x16x32_bf16 v[68:71], v[148:151], v[210:213], v[68:71]
	v_mfma_f32_16x16x32_bf16 v[64:67], v[156:159], v[210:213], v[64:67]
	s_setprio 0
	s_barrier
	s_add_i32 s59, s53, s43
	v_lshl_add_u64 v[214:215], s[38:39], 0, v[188:189]
	s_mov_b32 m0, s59
	ds_read_b128 v[160:163], v239 offset:16384
	ds_read_b128 v[164:167], v239 offset:17408
	ds_read_b128 v[168:171], v239 offset:18432
	ds_read_b128 v[172:175], v239 offset:19456
	ds_read_b128 v[176:179], v239 offset:20480
	ds_read_b128 v[180:183], v239 offset:21504
	ds_read_b128 v[206:209], v239 offset:22528
	ds_read_b128 v[210:213], v239 offset:23552
	global_load_lds_dwordx4 v[214:215], off
	s_add_i32 m0, s59, 0x2000
	s_add_u32 s60, s38, 0x40000
	v_lshl_add_u64 v[216:217], s[38:39], 0, v[192:193]
	s_addc_u32 s61, s39, 0
	s_add_i32 s59, s54, s43
	global_load_lds_dwordx4 v[216:217], off
	v_lshl_add_u64 v[218:219], s[60:61], 0, v[188:189]
	s_mov_b32 m0, s59
	v_lshl_add_u64 v[220:221], s[40:41], 0, v[190:191]
	global_load_lds_dwordx4 v[218:219], off
	v_lshl_add_u64 v[218:219], s[60:61], 0, v[192:193]
	s_add_i32 m0, s59, 0x2000
	s_nop 0
	global_load_lds_dwordx4 v[218:219], off
	v_lshl_add_u64 v[218:219], s[40:41], 0, v[186:187]
	s_mov_b32 m0, s44
	s_nop 0
	global_load_lds_dwordx4 v[218:219], off
	s_mov_b32 m0, s45
	s_nop 0
	global_load_lds_dwordx4 v[220:221], off
	s_waitcnt vmcnt(8)
	s_waitcnt lgkmcnt(0)
	s_barrier
; #define PG8_STAGE(bufoff, gbase, voff) do { _Pragma("unroll") for (int _i = 0; _i < 2; ++_i) \
;         __builtin_amdgcn_global_load_lds((const unsigned*)((const char*)(gbase) + (voff)[_i]), (PG8_LAS unsigned*)(lds + (bufoff) + ldsw + _i * 8192), 16, 0, 0); } while (0)
; #define PG8_LDA(dst, b, h) do { _Pragma("unroll") for (int m = 0; m < 4; ++m) _Pragma("unroll") for (int k = 0; k < 2; ++k) dst[m][k] = *(const PG8_LAS bf16x8*)(lds + PG8_SA(b, h) + aoff + m * 2048 + k * 1024); } while (0)
; #define PG8_LDB(dst, b, h) do { _Pragma("unroll") for (int n = 0; n < 2; ++n) _Pragma("unroll") for (int k = 0; k < 2; ++k) dst[n][k] = *(const PG8_LAS bf16x8*)(lds + PG8_SB(b, h) + boff + n * 2048 + k * 1024); } while (0)
; #define PG8_MMA(ai, bj, At, Bt) do { __builtin_amdgcn_s_setprio(1); _Pragma("unroll") for (int m = 0; m < 4; ++m) _Pragma("unroll") for (int n = 0; n < 2; ++n) _Pragma("unroll") for (int k = 0; k < 2; ++k) \
;         acc[ai][bj][m][n] = __builtin_amdgcn_mfma_f32_16x16x32_bf16(Bt[n][k], At[m][k], acc[ai][bj][m][n], 0, 0, 0); __builtin_amdgcn_s_setprio(0); } while (0)
; #define PG8_WAIT_V(n) asm volatile("s_waitcnt vmcnt(" #n ")" ::: "memory")
; template <class Epi, class Sched, bool ALIGN_EPI = false, bool SP2 = false>
; __device__ __forceinline__ void gemm_phase(PG8_LAS unsigned char* lds, const Gemm g, const Sched& S, const Epi& E) {
;     ...
;             PG8_LDB(B0, 0, 0); PG8_LDB(B1, 0, 1); PG8_SCHED; PG8_LDA(At, 0, 0); PG8_STAGE(PG8_SA(1, 1), a1 + hstepA, voffA);
;             PG8_WAIT_V(8); PG8_WAIT_L(0); PG8_BAR; PG8_MMA(0, 0, At, B0); PG8_MMA(0, 1, At, B1); PG8_BAR; PG8_SCHED;
;             PG8_LDA(At, 0, 1); PG8_STAGE(PG8_SB(0, 0), b2, voffB); PG8_STAGE(PG8_SB(0, 1), b2 + hstepB, voffB); PG8_STAGE(PG8_SA(0, 0), a2, voffA);
;             PG8_WAIT_V(8); PG8_WAIT_L(0); PG8_BAR; PG8_MMA(1, 0, At, B0); PG8_MMA(1, 1, At, B1); PG8_BAR; PG8_SCHED;
;             PG8_LDB(B0, 1, 0); PG8_LDB(B1, 1, 1); PG8_SCHED; PG8_LDA(At, 1, 0); PG8_STAGE(PG8_SA(0, 1), a2 + hstepA, voffA);
;             PG8_WAIT_V(8); PG8_WAIT_L(0); PG8_BAR; PG8_MMA(0, 0, At, B0); PG8_MMA(0, 1, At, B1); PG8_BAR; PG8_SCHED;
;             PG8_LDA(At, 1, 1); PG8_STAGE(PG8_SB(1, 0), b3, voffB); PG8_STAGE(PG8_SB(1, 1), b3 + hstepB, voffB); PG8_STAGE(PG8_SA(1, 0), a3, voffA);
;             PG8_WAIT_V(8); PG8_WAIT_L(0); PG8_BAR; PG8_MMA(1, 0, At, B0); PG8_MMA(1, 1, At, B1); PG8_BAR; PG8_SCHED;
	s_setprio 1
	s_waitcnt lgkmcnt(0)
	v_mfma_f32_16x16x32_bf16 v[60:63], v[120:123], v[160:163], v[60:63]
	v_mfma_f32_16x16x32_bf16 v[56:59], v[136:139], v[160:163], v[56:59]
	v_mfma_f32_16x16x32_bf16 v[44:47], v[120:123], v[168:171], v[44:47]
	v_mfma_f32_16x16x32_bf16 v[40:43], v[136:139], v[168:171], v[40:43]
	v_mfma_f32_16x16x32_bf16 v[28:31], v[120:123], v[176:179], v[28:31]
	v_mfma_f32_16x16x32_bf16 v[24:27], v[136:139], v[176:179], v[24:27]
	v_mfma_f32_16x16x32_bf16 v[12:15], v[120:123], v[206:209], v[12:15]
	v_mfma_f32_16x16x32_bf16 v[8:11], v[136:139], v[206:209], v[8:11]
	v_mfma_f32_16x16x32_bf16 v[60:63], v[124:127], v[164:167], v[60:63]
	v_mfma_f32_16x16x32_bf16 v[56:59], v[140:143], v[164:167], v[56:59]
	v_mfma_f32_16x16x32_bf16 v[44:47], v[124:127], v[172:175], v[44:47]
	v_mfma_f32_16x16x32_bf16 v[40:43], v[140:143], v[172:175], v[40:43]
	v_mfma_f32_16x16x32_bf16 v[28:31], v[124:127], v[180:183], v[28:31]
	v_mfma_f32_16x16x32_bf16 v[24:27], v[140:143], v[180:183], v[24:27]
	v_mfma_f32_16x16x32_bf16 v[12:15], v[124:127], v[210:213], v[12:15]
	v_mfma_f32_16x16x32_bf16 v[8:11], v[140:143], v[210:213], v[8:11]
	s_setprio 0
	s_setprio 1
	v_mfma_f32_16x16x32_bf16 v[52:55], v[144:147], v[160:163], v[52:55]
	v_mfma_f32_16x16x32_bf16 v[48:51], v[152:155], v[160:163], v[48:51]
	v_mfma_f32_16x16x32_bf16 v[36:39], v[144:147], v[168:171], v[36:39]
	v_mfma_f32_16x16x32_bf16 v[32:35], v[152:155], v[168:171], v[32:35]
	v_mfma_f32_16x16x32_bf16 v[20:23], v[144:147], v[176:179], v[20:23]
	v_mfma_f32_16x16x32_bf16 v[16:19], v[152:155], v[176:179], v[16:19]
	v_mfma_f32_16x16x32_bf16 v[4:7], v[144:147], v[206:209], v[4:7]
	v_mfma_f32_16x16x32_bf16 v[0:3], v[152:155], v[206:209], v[0:3]
	v_mfma_f32_16x16x32_bf16 v[52:55], v[148:151], v[164:167], v[52:55]
	v_mfma_f32_16x16x32_bf16 v[48:51], v[156:159], v[164:167], v[48:51]
	v_mfma_f32_16x16x32_bf16 v[36:39], v[148:151], v[172:175], v[36:39]
	v_mfma_f32_16x16x32_bf16 v[32:35], v[156:159], v[172:175], v[32:35]
	v_mfma_f32_16x16x32_bf16 v[20:23], v[148:151], v[180:183], v[20:23]
	v_mfma_f32_16x16x32_bf16 v[16:19], v[156:159], v[180:183], v[16:19]
	v_mfma_f32_16x16x32_bf16 v[4:7], v[148:151], v[210:213], v[4:7]
	v_mfma_f32_16x16x32_bf16 v[0:3], v[156:159], v[210:213], v[0:3]
	s_setprio 0
	s_barrier
	s_add_i32 s59, 0, 0x18000
	s_add_i32 s60, 0, 0x1c000
	v_add_u32_e32 v140, s59, v234
	v_add_u32_e32 v156, s60, v234
	ds_read_b128 v[120:123], v140
	ds_read_b128 v[124:127], v140 offset:1024
	ds_read_b128 v[136:139], v140 offset:2048
	ds_read_b128 v[140:143], v140 offset:3072
	ds_read_b128 v[144:147], v156
	ds_read_b128 v[148:151], v156 offset:1024
	ds_read_b128 v[152:155], v156 offset:2048
	ds_read_b128 v[156:159], v156 offset:3072
	s_add_u32 s40, s40, 0x40000
	s_addc_u32 s41, s41, 0
	s_mov_b32 m0, s46
	v_lshl_add_u64 v[222:223], s[40:41], 0, v[186:187]
	ds_read_b128 v[160:163], v239 offset:32768
	ds_read_b128 v[164:167], v239 offset:33792
	ds_read_b128 v[168:171], v239 offset:34816
	ds_read_b128 v[172:175], v239 offset:35840
	ds_read_b128 v[176:179], v239 offset:36864
	ds_read_b128 v[180:183], v239 offset:37888
	ds_read_b128 v[206:209], v239 offset:38912
	ds_read_b128 v[210:213], v239 offset:39936
	global_load_lds_dwordx4 v[222:223], off
	v_lshl_add_u64 v[222:223], s[40:41], 0, v[190:191]
	s_mov_b32 m0, s47
	s_nop 0
	global_load_lds_dwordx4 v[222:223], off
	s_waitcnt vmcnt(8)
	s_waitcnt lgkmcnt(0)
	s_barrier
	s_setprio 1
	s_waitcnt lgkmcnt(0)
	v_mfma_f32_16x16x32_bf16 v[132:135], v[120:123], v[160:163], v[132:135]
	v_mfma_f32_16x16x32_bf16 v[128:131], v[136:139], v[160:163], v[128:131]
	v_mfma_f32_16x16x32_bf16 v[108:111], v[120:123], v[168:171], v[108:111]
	v_mfma_f32_16x16x32_bf16 v[104:107], v[136:139], v[168:171], v[104:107]
	v_mfma_f32_16x16x32_bf16 v[92:95], v[120:123], v[176:179], v[92:95]
	v_mfma_f32_16x16x32_bf16 v[88:91], v[136:139], v[176:179], v[88:91]
	v_mfma_f32_16x16x32_bf16 v[76:79], v[120:123], v[206:209], v[76:79]
	v_mfma_f32_16x16x32_bf16 v[72:75], v[136:139], v[206:209], v[72:75]
	v_mfma_f32_16x16x32_bf16 v[132:135], v[124:127], v[164:167], v[132:135]
	v_mfma_f32_16x16x32_bf16 v[128:131], v[140:143], v[164:167], v[128:131]
	v_mfma_f32_16x16x32_bf16 v[108:111], v[124:127], v[172:175], v[108:111]
	v_mfma_f32_16x16x32_bf16 v[104:107], v[140:143], v[172:175], v[104:107]
	v_mfma_f32_16x16x32_bf16 v[92:95], v[124:127], v[180:183], v[92:95]
	v_mfma_f32_16x16x32_bf16 v[88:91], v[140:143], v[180:183], v[88:91]
	v_mfma_f32_16x16x32_bf16 v[76:79], v[124:127], v[210:213], v[76:79]
	v_mfma_f32_16x16x32_bf16 v[72:75], v[140:143], v[210:213], v[72:75]
	s_setprio 0
	s_setprio 1
	v_mfma_f32_16x16x32_bf16 v[116:119], v[144:147], v[160:163], v[116:119]
	v_mfma_f32_16x16x32_bf16 v[112:115], v[152:155], v[160:163], v[112:115]
	v_mfma_f32_16x16x32_bf16 v[100:103], v[144:147], v[168:171], v[100:103]
	v_mfma_f32_16x16x32_bf16 v[96:99], v[152:155], v[168:171], v[96:99]
	v_mfma_f32_16x16x32_bf16 v[84:87], v[144:147], v[176:179], v[84:87]
	v_mfma_f32_16x16x32_bf16 v[80:83], v[152:155], v[176:179], v[80:83]
	v_mfma_f32_16x16x32_bf16 v[68:71], v[144:147], v[206:209], v[68:71]
	v_mfma_f32_16x16x32_bf16 v[64:67], v[152:155], v[206:209], v[64:67]
	v_mfma_f32_16x16x32_bf16 v[116:119], v[148:151], v[164:167], v[116:119]
	v_mfma_f32_16x16x32_bf16 v[112:115], v[156:159], v[164:167], v[112:115]
	v_mfma_f32_16x16x32_bf16 v[100:103], v[148:151], v[172:175], v[100:103]
	v_mfma_f32_16x16x32_bf16 v[96:99], v[156:159], v[172:175], v[96:99]
	v_mfma_f32_16x16x32_bf16 v[84:87], v[148:151], v[180:183], v[84:87]
	v_mfma_f32_16x16x32_bf16 v[80:83], v[156:159], v[180:183], v[80:83]
	v_mfma_f32_16x16x32_bf16 v[68:71], v[148:151], v[210:213], v[68:71]
	v_mfma_f32_16x16x32_bf16 v[64:67], v[156:159], v[210:213], v[64:67]
	s_setprio 0
	s_barrier
; #define PG8_WAIT_V(n) asm volatile("s_waitcnt vmcnt(" #n ")" ::: "memory")
; template <class Epi, class Sched, bool ALIGN_EPI = false, bool SP2 = false>
; __device__ __forceinline__ void gemm_phase(PG8_LAS unsigned char* lds, const Gemm g, const Sched& S, const Epi& E) {
;     ...
;         for (int t = 0; t < nt; t += 2) {
;             const bool last = (t == nt - 2);
;             const char* a1 = cA + (size_t)(t + 1) * kstep;
;             const char* a2 = last ? nA : cA + (size_t)(t + 2) * kstep; const char* b2 = last ? nB : cB + (size_t)(t + 2) * kstep;
;             const char* a3 = a2 + kstep; const char* b3 = b2 + kstep;
;             if (last && has_next) S.a_ready(nxt);
;             if constexpr (SP2) {
;             PG8_LDB(B0, 0, 0); PG8_LDB(B1, 0, 1); PG8_SCHED; PG8_LDA(At, 0, 0); PG8_STAGE(PG8_SA(1, 1), a1 + hstepA, voffA);
;             PG8_WAIT_V(8); PG8_WAIT_L(0); PG8_BAR; PG8_MMA(0, 0, At, B0); PG8_MMA(0, 1, At, B1); PG8_BAR; PG8_SCHED;
;             PG8_LDA(At, 0, 1); PG8_STAGE(PG8_SB(0, 0), b2, voffB); PG8_STAGE(PG8_SB(0, 1), b2 + hstepB, voffB); PG8_STAGE(PG8_SA(0, 0), a2, voffA);
;             PG8_WAIT_V(8); PG8_WAIT_L(0); PG8_BAR; PG8_MMA(1, 0, At, B0); PG8_MMA(1, 1, At, B1); PG8_BAR; PG8_SCHED;
;             PG8_LDB(B0, 1, 0); PG8_LDB(B1, 1, 1); PG8_SCHED; PG8_LDA(At, 1, 0); PG8_STAGE(PG8_SA(0, 1), a2 + hstepA, voffA);
;             PG8_WAIT_V(8); PG8_WAIT_L(0); PG8_BAR; PG8_MMA(0, 0, At, B0); PG8_MMA(0, 1, At, B1); PG8_BAR; PG8_SCHED;
;             PG8_LDA(At, 1, 1); PG8_STAGE(PG8_SB(1, 0), b3, voffB); PG8_STAGE(PG8_SB(1, 1), b3 + hstepB, voffB); PG8_STAGE(PG8_SA(1, 0), a3, voffA);
;             PG8_WAIT_V(8); PG8_WAIT_L(0); PG8_BAR; PG8_MMA(1, 0, At, B0); PG8_MMA(1, 1, At, B1); PG8_BAR; PG8_SCHED;
;             } else {
;             PG8_LDB(B0, 0, 0); PG8_SCHED; PG8_LDA(At, 0, 0); PG8_STAGE(PG8_SA(1, 1), a1 + hstepA, voffA);
;             PG8_WAIT_L(8); PG8_BAR; PG8_WAIT_L(0); PG8_MMA(0, 0, At, B0); PG8_BAR; PG8_SCHED;
;             PG8_LDB(B1, 0, 1); PG8_STAGE(PG8_SB(0, 0), b2, voffB);
;             PG8_BAR; PG8_WAIT_L(0); PG8_MMA(0, 1, At, B1); PG8_BAR;
;             PG8_LDA(At, 0, 1); PG8_STAGE(PG8_SA(0, 0), a2, voffA);
;             PG8_BAR; PG8_WAIT_L(0); PG8_MMA(1, 0, At, B0); PG8_BAR; PG8_SCHED;
;             PG8_STAGE(PG8_SB(0, 1), b2 + hstepB, voffB);
;             PG8_WAIT_V(6); PG8_BAR; PG8_MMA(1, 1, At, B1); PG8_BAR;
	s_add_i32 s40, s59, s43
	v_lshl_add_u64 v[214:215], v[214:215], 0, s[20:21]
	s_mov_b32 m0, s40
	ds_read_b128 v[160:163], v239 offset:49152
	ds_read_b128 v[164:167], v239 offset:50176
	ds_read_b128 v[168:171], v239 offset:51200
	ds_read_b128 v[172:175], v239 offset:52224
	ds_read_b128 v[176:179], v239 offset:53248
	ds_read_b128 v[180:183], v239 offset:54272
	ds_read_b128 v[206:209], v239 offset:55296
	ds_read_b128 v[210:213], v239 offset:56320
	global_load_lds_dwordx4 v[214:215], off
	s_add_i32 m0, s40, 0x2000
	s_add_u32 s38, s38, 0x40080
	v_lshl_add_u64 v[214:215], v[216:217], 0, s[20:21]
	s_addc_u32 s39, s39, 0
	s_add_i32 s40, s60, s43
	global_load_lds_dwordx4 v[214:215], off
	v_lshl_add_u64 v[214:215], s[38:39], 0, v[188:189]
	s_mov_b32 m0, s40
	s_nop 0
	global_load_lds_dwordx4 v[214:215], off
	v_lshl_add_u64 v[214:215], s[38:39], 0, v[192:193]
	s_add_i32 m0, s40, 0x2000
	s_nop 0
	global_load_lds_dwordx4 v[214:215], off
	v_lshl_add_u64 v[214:215], v[218:219], 0, s[20:21]
	s_mov_b32 m0, s48
	s_nop 0
	global_load_lds_dwordx4 v[214:215], off
	v_lshl_add_u64 v[214:215], v[220:221], 0, s[20:21]
	s_mov_b32 m0, s49
	s_nop 0
	global_load_lds_dwordx4 v[214:215], off
	s_waitcnt vmcnt(8)
	s_waitcnt lgkmcnt(0)
	s_barrier
	s_setprio 1
	s_waitcnt lgkmcnt(0)
	v_mfma_f32_16x16x32_bf16 v[60:63], v[120:123], v[160:163], v[60:63]
	v_mfma_f32_16x16x32_bf16 v[56:59], v[136:139], v[160:163], v[56:59]
	v_mfma_f32_16x16x32_bf16 v[44:47], v[120:123], v[168:171], v[44:47]
	v_mfma_f32_16x16x32_bf16 v[40:43], v[136:139], v[168:171], v[40:43]
	v_mfma_f32_16x16x32_bf16 v[28:31], v[120:123], v[176:179], v[28:31]
	v_mfma_f32_16x16x32_bf16 v[24:27], v[136:139], v[176:179], v[24:27]
	v_mfma_f32_16x16x32_bf16 v[12:15], v[120:123], v[206:209], v[12:15]
	v_mfma_f32_16x16x32_bf16 v[8:11], v[136:139], v[206:209], v[8:11]
	v_mfma_f32_16x16x32_bf16 v[60:63], v[124:127], v[164:167], v[60:63]
	v_mfma_f32_16x16x32_bf16 v[56:59], v[140:143], v[164:167], v[56:59]
	v_mfma_f32_16x16x32_bf16 v[44:47], v[124:127], v[172:175], v[44:47]
	v_mfma_f32_16x16x32_bf16 v[40:43], v[140:143], v[172:175], v[40:43]
	v_mfma_f32_16x16x32_bf16 v[28:31], v[124:127], v[180:183], v[28:31]
	v_mfma_f32_16x16x32_bf16 v[24:27], v[140:143], v[180:183], v[24:27]
	v_mfma_f32_16x16x32_bf16 v[12:15], v[124:127], v[210:213], v[12:15]
	v_mfma_f32_16x16x32_bf16 v[8:11], v[140:143], v[210:213], v[8:11]
	s_setprio 0
	s_setprio 1
	v_mfma_f32_16x16x32_bf16 v[52:55], v[144:147], v[160:163], v[52:55]
	v_mfma_f32_16x16x32_bf16 v[48:51], v[152:155], v[160:163], v[48:51]
	v_mfma_f32_16x16x32_bf16 v[36:39], v[144:147], v[168:171], v[36:39]
	v_mfma_f32_16x16x32_bf16 v[32:35], v[152:155], v[168:171], v[32:35]
	v_mfma_f32_16x16x32_bf16 v[20:23], v[144:147], v[176:179], v[20:23]
	v_mfma_f32_16x16x32_bf16 v[16:19], v[152:155], v[176:179], v[16:19]
	v_mfma_f32_16x16x32_bf16 v[4:7], v[144:147], v[206:209], v[4:7]
	v_mfma_f32_16x16x32_bf16 v[0:3], v[152:155], v[206:209], v[0:3]
	v_mfma_f32_16x16x32_bf16 v[52:55], v[148:151], v[164:167], v[52:55]
	v_mfma_f32_16x16x32_bf16 v[48:51], v[156:159], v[164:167], v[48:51]
	v_mfma_f32_16x16x32_bf16 v[36:39], v[148:151], v[172:175], v[36:39]
	v_mfma_f32_16x16x32_bf16 v[32:35], v[156:159], v[172:175], v[32:35]
	v_mfma_f32_16x16x32_bf16 v[20:23], v[148:151], v[180:183], v[20:23]
	v_mfma_f32_16x16x32_bf16 v[16:19], v[156:159], v[180:183], v[16:19]
	v_mfma_f32_16x16x32_bf16 v[4:7], v[148:151], v[210:213], v[4:7]
	v_mfma_f32_16x16x32_bf16 v[0:3], v[156:159], v[210:213], v[0:3]
	s_setprio 0
	s_barrier
	s_add_i32 s58, s58, 2
	s_add_u32 s36, s36, 0x100
	s_addc_u32 s37, s37, 0
	s_add_u32 s56, s56, 0x100
	s_addc_u32 s57, s57, 0
	s_cmp_gt_u32 s58, 13
	s_cbranch_scc0 .LBB0_935
	s_and_b64 vcc, exec, s[22:23]
	s_cbranch_vccz .LBB0_938
	s_barrier
.LBB0_938:
	s_cmp_eq_u32 s98, 1
	s_cbranch_scc1 .Lx_ok
.Lx_poll:
	v_mov_b32_e32 v250, 0
	global_load_dword v250, v250, s[100:101] sc1
	s_waitcnt vmcnt(0)
	v_readfirstlane_b32 s99, v250
	s_cmp_ge_u32 s99, s88
	s_cbranch_scc1 .Lx_set
	s_sleep 1
	s_branch .Lx_poll
.Lx_set:
	s_mov_b32 s98, 1
;     __device__ __forceinline__ void operator()(const f32x4 (&acc)[2][2][4][2], const pg8::Unit& u, int wr, int wc, int fr, int fq) const {
;         u32x4 xr[2][4][2];
; #pragma unroll
;         for (int ai = 0; ai < 2; ++ai)
; #pragma unroll
;             for (int m = 0; m < 4; ++m)
; #pragma unroll
;                 for (int bj = 0; bj < 2; ++bj)
;                     xr[ai][m][bj] = *(const u32x4*)(xb + (size_t)(u.pm * 256 + ai * 128 + wr * 64 + m * 16 + fr) * DM + u.pn * 256 + 128 * bj + 32 * wc + 8 * fq);
;         __builtin_amdgcn_sched_barrier(0);
; #pragma unroll
;         for (int ai = 0; ai < 2; ++ai)
; #pragma unroll
;             for (int m = 0; m < 4; ++m) {
;                 const int row = u.pm * 256 + ai * 128 + wr * 64 + m * 16 + fr;
;                 float ss = 0.f;
; #pragma unroll
;                 for (int bj = 0; bj < 2; ++bj) {
;                     const size_t off = (size_t)row * DM + u.pn * 256 + 128 * bj + 32 * wc + 8 * fq;
;                     const u32x4 w = xr[ai][m][bj];
;                     float y[8];
;                     y[0] = __uint_as_float(w.x << 16) + acc[ai][bj][m][0].x; y[1] = __uint_as_float(w.x & 0xffff0000u) + acc[ai][bj][m][0].y;
;                     y[2] = __uint_as_float(w.y << 16) + acc[ai][bj][m][0].z; y[3] = __uint_as_float(w.y & 0xffff0000u) + acc[ai][bj][m][0].w;
;                     y[4] = __uint_as_float(w.z << 16) + acc[ai][bj][m][1].x; y[5] = __uint_as_float(w.z & 0xffff0000u) + acc[ai][bj][m][1].y;
;                     y[6] = __uint_as_float(w.w << 16) + acc[ai][bj][m][1].z; y[7] = __uint_as_float(w.w & 0xffff0000u) + acc[ai][bj][m][1].w;
;                     store8(x2b + off, y);
; #pragma unroll
;                     for (int i = 0; i < 8; ++i) ss += y[i] * y[i];
;                 }
;                 ss += __shfl_xor(ss, 16); ss += __shfl_xor(ss, 32);
;                 if (fq == 0) red[wc * 256 + (row & 255)] = ss;
;             }
.Lx_ok:
	s_lshl_b32 s9, s34, 8
	s_lshl_b32 s34, s8, 8
	v_add_u32_e32 v120, s9, v185
	s_ashr_i32 s35, s34, 31
	s_lshl_b64 s[36:37], s[34:35], 1
	v_ashrrev_i32_e32 v121, 31, v120
	v_or_b32_e32 v230, 16, v120
	v_lshl_add_u64 v[122:123], v[196:197], 0, s[36:37]
	v_lshlrev_b64 v[250:251], 11, v[120:121]
	v_ashrrev_i32_e32 v231, 31, v230
	v_or_b32_e32 v226, 32, v120
	v_lshl_add_u64 v[124:125], v[122:123], 0, v[250:251]
	v_lshlrev_b64 v[232:233], 11, v[230:231]
	v_ashrrev_i32_e32 v227, 31, v226
	v_or_b32_e32 v222, 48, v120
	global_load_dwordx4 v[242:245], v[124:125], off
	global_load_dwordx4 v[246:249], v[124:125], off offset:256
	v_lshl_add_u64 v[124:125], v[122:123], 0, v[232:233]
	v_lshlrev_b64 v[228:229], 11, v[226:227]
	v_ashrrev_i32_e32 v223, 31, v222
	v_add_u32_e32 v218, 0x80, v120
	global_load_dwordx4 v[180:183], v[124:125], off
	global_load_dwordx4 v[176:179], v[124:125], off offset:256
	v_lshl_add_u64 v[124:125], v[122:123], 0, v[228:229]
	v_lshlrev_b64 v[224:225], 11, v[222:223]
	v_ashrrev_i32_e32 v219, 31, v218
	v_add_u32_e32 v214, 0x90, v120
	global_load_dwordx4 v[172:175], v[124:125], off
	global_load_dwordx4 v[168:171], v[124:125], off offset:256
	v_lshl_add_u64 v[124:125], v[122:123], 0, v[224:225]
	v_lshlrev_b64 v[220:221], 11, v[218:219]
	v_ashrrev_i32_e32 v215, 31, v214
	v_add_u32_e32 v210, 0xa0, v120
	v_add_u32_e32 v206, 0xb0, v120
	global_load_dwordx4 v[164:167], v[124:125], off
	global_load_dwordx4 v[160:163], v[124:125], off offset:256
	v_lshl_add_u64 v[124:125], v[122:123], 0, v[220:221]
	v_lshlrev_b64 v[216:217], 11, v[214:215]
	v_ashrrev_i32_e32 v211, 31, v210
	v_ashrrev_i32_e32 v207, 31, v206
	global_load_dwordx4 v[156:159], v[124:125], off
	global_load_dwordx4 v[152:155], v[124:125], off offset:256
	v_lshl_add_u64 v[124:125], v[122:123], 0, v[216:217]
	v_lshlrev_b64 v[212:213], 11, v[210:211]
	v_lshlrev_b64 v[208:209], 11, v[206:207]
	global_load_dwordx4 v[148:151], v[124:125], off
	global_load_dwordx4 v[144:147], v[124:125], off offset:256
	v_lshl_add_u64 v[124:125], v[122:123], 0, v[212:213]
	v_lshl_add_u64 v[120:121], v[122:123], 0, v[208:209]
	global_load_dwordx4 v[140:143], v[124:125], off
	global_load_dwordx4 v[136:139], v[124:125], off offset:256
	s_nop 0
	global_load_dwordx4 v[124:127], v[120:121], off
	s_nop 0
	global_load_dwordx4 v[120:123], v[120:121], off offset:256
	s_waitcnt vmcnt(0)
	v_lshlrev_b32_e32 v207, 16, v242
	v_add_f32_e32 v207, v132, v207
	v_and_b32_e32 v132, 0xffff0000, v242
	v_add_f32_e32 v211, v133, v132
	v_lshlrev_b32_e32 v132, 16, v243
	v_add_f32_e32 v134, v134, v132
	v_and_b32_e32 v132, 0xffff0000, v243
	v_add_f32_e32 v135, v135, v132
	v_lshlrev_b32_e32 v132, 16, v244
	v_add_f32_e32 v215, v128, v132
	v_and_b32_e32 v128, 0xffff0000, v244
	v_add_f32_e32 v219, v129, v128
	v_lshlrev_b32_e32 v128, 16, v245
	v_add_f32_e32 v223, v130, v128
	v_and_b32_e32 v128, 0xffff0000, v245
	v_add_f32_e32 v131, v131, v128
	v_lshl_add_u64 v[128:129], s[16:17], 0, v[250:251]
	v_lshl_add_u64 v[128:129], v[128:129], 0, s[36:37]
	v_lshl_add_u64 v[128:129], v[128:129], 0, s[10:11]
	v_lshl_add_u64 v[132:133], v[128:129], 0, v[194:195]
	v_cvt_pk_bf16_f32 v128, v207, v211
	v_mul_f32_e32 v211, v211, v211
	v_fmac_f32_e32 v211, v207, v207
	v_fmac_f32_e32 v211, v134, v134
	v_fmac_f32_e32 v211, v135, v135
	v_fmac_f32_e32 v211, v215, v215
	v_lshlrev_b32_e32 v130, 16, v246
	v_fmac_f32_e32 v211, v219, v219
	v_add_f32_e32 v116, v116, v130
	v_and_b32_e32 v130, 0xffff0000, v246
	v_fmac_f32_e32 v211, v223, v223
	v_add_f32_e32 v117, v117, v130
	v_lshlrev_b32_e32 v130, 16, v247
	v_fmac_f32_e32 v211, v131, v131
	v_add_f32_e32 v118, v118, v130
	v_and_b32_e32 v130, 0xffff0000, v247
	v_add_f32_e32 v119, v119, v130
	v_lshlrev_b32_e32 v130, 16, v248
	v_fmac_f32_e32 v211, v116, v116
	v_cvt_pk_bf16_f32 v129, v134, v135
	v_add_f32_e32 v134, v112, v130
	v_and_b32_e32 v112, 0xffff0000, v248
	v_fmac_f32_e32 v211, v117, v117
	v_add_f32_e32 v135, v113, v112
	v_lshlrev_b32_e32 v112, 16, v249
	v_fmac_f32_e32 v211, v118, v118
	v_add_f32_e32 v207, v114, v112
	v_and_b32_e32 v112, 0xffff0000, v249
	v_fmac_f32_e32 v211, v119, v119
	v_and_b32_e32 v113, 64, v240
	v_add_f32_e32 v227, v115, v112
	v_fmac_f32_e32 v211, v134, v134
	v_xor_b32_e32 v112, 16, v240
	v_add_u32_e32 v113, 64, v113
	v_fmac_f32_e32 v211, v135, v135
	v_cmp_lt_i32_e32 vcc, v112, v113
	v_fmac_f32_e32 v211, v207, v207
	v_fmac_f32_e32 v211, v227, v227
	v_cndmask_b32_e32 v112, v240, v112, vcc
	v_lshlrev_b32_e32 v112, 2, v112
	ds_bpermute_b32 v114, v112, v211
	v_xor_b32_e32 v115, 32, v240
	v_cmp_lt_i32_e32 vcc, v115, v113
	v_cvt_pk_bf16_f32 v130, v215, v219
	v_cvt_pk_bf16_f32 v131, v223, v131
	s_waitcnt lgkmcnt(0)
	v_add_f32_e32 v114, v211, v114
	global_store_dwordx4 v[132:133], v[128:131], off
	v_cndmask_b32_e32 v113, v240, v115, vcc
	v_lshlrev_b32_e32 v113, 2, v113
	ds_bpermute_b32 v115, v113, v114
	v_cvt_pk_bf16_f32 v116, v116, v117
	v_cvt_pk_bf16_f32 v117, v118, v119
	v_cvt_pk_bf16_f32 v118, v134, v135
	v_cvt_pk_bf16_f32 v119, v207, v227
	global_store_dwordx4 v[132:133], v[116:119], off offset:256
	s_and_saveexec_b64 s[36:37], s[2:3]
	s_cbranch_execz .LBB0_940
	s_waitcnt lgkmcnt(0)
	v_add_f32_e32 v114, v114, v115
	ds_write_b32 v235, v114

; #define LAS __attribute__((address_space(3)))
; __device__ __forceinline__ unsigned xb_ld(unsigned* p) { return __hip_atomic_load(p, __ATOMIC_RELAXED, __HIP_MEMORY_SCOPE_AGENT); }
; __device__ __forceinline__ unsigned xb_add(unsigned* p, unsigned v) { return __hip_atomic_fetch_add(p, v, __ATOMIC_RELAXED, __HIP_MEMORY_SCOPE_AGENT); }
; __device__ __forceinline__ unsigned xb_xcc_id() { return (unsigned)__builtin_amdgcn_s_getreg((3 << 11) | 20) & 0xFu; }
; __device__ __forceinline__ void grid_barrier(unsigned* barw, int k, volatile LAS unsigned* st) {
;     asm volatile("s_waitcnt vmcnt(0)" ::: "memory");
;     __syncthreads();
;     if (threadIdx.x == 0) {
;         __builtin_amdgcn_s_waitcnt(0);
;         const unsigned x = xb_xcc_id();
;         unsigned nloc = st[0], nx = st[1];
;         if (nloc == 0u) {
;             const unsigned G = gridDim.x;
;             for (;;) { unsigned sum = 0u, cnt = 0u, mine = 0u;
; #pragma unroll
;                 for (unsigned j = 0; j < 16; ++j) { const unsigned c = xb_ld(barw + 64 * j); sum += c; cnt += (c > 0u) ? 1u : 0u; mine = (j == x) ? c : mine; }
;                 if (sum == G) { nloc = mine; nx = cnt; break; }
;                 __builtin_amdgcn_s_sleep(1); }
;             st[0] = nloc; st[1] = nx;
;         }
;         unsigned* sb = barw + 1024 + k * 2304;
;         const unsigned old = xb_add(sb + 64 * x, 1u);
;         if (old + 1u == nloc) {
;             __builtin_amdgcn_fence(__ATOMIC_RELEASE, "agent");
;             asm volatile("s_waitcnt vmcnt(0)" ::: "memory");
;             const unsigned og = xb_add(sb + 2048, 1u);
;             if (og + 1u == nx) xb_add(sb + 2112, 1u);
;             else while (xb_ld(sb + 2112) == 0u) __builtin_amdgcn_s_sleep(1);
;             __builtin_amdgcn_fence(__ATOMIC_ACQUIRE, "agent");
;             xb_add(sb + 1024 + 64 * x, 1u);
;             asm volatile("s_waitcnt vmcnt(0)" ::: "memory");
;         } else {
;             while (xb_ld(sb + 1024 + 64 * x) == 0u) __builtin_amdgcn_s_sleep(1);
;             __builtin_amdgcn_fence(__ATOMIC_ACQUIRE, "agent");
;             asm volatile("s_waitcnt vmcnt(0)" ::: "memory");
;         }
;     }
;     __syncthreads();
; }
.LBB0_960:
	v_readlane_b32 s2, v254, 0
	v_readlane_b32 s3, v254, 1
	s_cmp_gt_i32 s3, 6
	s_cselect_b64 s[72:73], -1, 0
	s_and_b64 s[0:1], s[0:1], s[72:73]
	s_andn2_b64 vcc, exec, s[0:1]
	s_cbranch_vccnz .LBB0_989
	s_waitcnt vmcnt(0)
	s_waitcnt vmcnt(0) lgkmcnt(0)
	s_barrier
	s_mov_b64 s[74:75], exec
	v_readlane_b32 s0, v254, 2
	v_readlane_b32 s1, v254, 3
	s_and_b64 s[0:1], s[74:75], s[0:1]
	s_mov_b64 exec, s[0:1]
	s_cbranch_execz .LBB0_988
	s_add_u32 s4, s78, 0x12f00
	s_addc_u32 s5, s79, 0
	v_mov_b32_e32 v0, 0
	v_mov_b32_e32 v1, 1
	global_atomic_add v0, v1, s[4:5]
	s_and_b32 s0, s88, 7
	s_cmp_lg_u32 s0, 0
	s_cbranch_scc1 .Lgb0_orig
	s_waitcnt vmcnt(0) lgkmcnt(0)
	s_and_b32 s0, s70, 7
	s_lshl_b32 s0, s0, 8
	s_add_i32 s0, s0, 0x10c00
	s_add_u32 s4, s78, s0
	s_addc_u32 s5, s79, 0
	s_lshr_b32 s6, s88, 3
	s_getreg_b32 s8, hwreg(HW_REG_XCC_ID, 0, 4)
	s_lshl_b32 s8, 1, s8
	v_mov_b32_e32 v0, 0
	v_mov_b32_e32 v1, s8
	global_atomic_or v2, v0, v1, s[4:5] offset:64 sc0
	s_waitcnt vmcnt(0)
	v_mov_b32_e32 v1, 1
	global_atomic_add v2, v0, v1, s[4:5] sc0
	s_waitcnt vmcnt(0)
	v_readfirstlane_b32 s7, v2
	s_add_i32 s7, s7, 1
	s_cmp_ge_u32 s7, s6
	s_cbranch_scc1 .Lgb0_all1

;     __device__ bool next(int i, Unit& u) const { const long L = (long)i * G + c; if (L >= 128) return false; u.pm = (int)L & 31; u.pn = u.pm >> 4; u.koff = ((int)L >> 5) * 1024; return true; }
;     __host__ __device__ bool next(int i, Unit& u) const {
;         const long L = (long)i * G + c; if (L >= nwg) return false;
;         int wgid = (int)L; { const int q = nwg / NXCD, r = nwg % NXCD, xcd = wgid % NXCD, off = wgid / NXCD; wgid = (xcd < r ? xcd * (q + 1) : r * (q + 1) + (xcd - r) * q) + off; }
;         const int nig = WGM * nN, gid = wgid / nig, fm = gid * WGM, gsz = (nM - fm) < WGM ? (nM - fm) : WGM;
;         u.pm = fm + ((wgid % nig) % gsz); u.pn = (wgid % nig) / gsz; u.koff = 0; return true;
; __global__ void __launch_bounds__(NWAVES * 64, 2) fwd_kernel(Args args) {
;     ...
;     if (IN(6)) {
;         pg8::Gemm g{(const bf16_t*)(ws + WS_X2B), (const bf16_t*)(ws + WS_WFF1), T, FF, DM, DM, DM};
;         pg8::StaticOrder So; So.init(T, FF, G, (int)blockIdx.x);
;         EpiFF1 E{(const float*)(ws + WS_SSQP), (bf16_t*)(ws + WS_H)};
;         pg8::gemm_phase<EpiFF1, pg8::StaticOrder, true, true>(lds, g, So, E);
.LBB0_989:
	s_mov_b32 s98, 0
	s_add_u32 s100, s78, 0x12f00
	s_addc_u32 s101, s79, 0
	v_readlane_b32 s0, v254, 0
	v_readlane_b32 s1, v254, 1
	s_cmp_lt_i32 s0, 7
	s_cselect_b64 s[0:1], -1, 0
	s_and_b64 s[0:1], s[0:1], s[72:73]
	s_andn2_b64 vcc, exec, s[0:1]
	s_cbranch_vccnz .LBB0_1014
	s_cmpk_gt_i32 s70, 0x7ff
	v_readfirstlane_b32 s4, v184
	s_cbranch_scc1 .LBB0_1014
	s_ashr_i32 s14, s70, 31
	s_lshr_b32 s2, s14, 29
	s_add_i32 s7, s70, s2
	s_and_b32 s2, s7, -8
	s_sub_i32 s6, s70, s2
	s_cmp_gt_i32 s6, -1
	s_cbranch_scc0 .LBB0_993
	s_lshl_b32 s5, s6, 8
	s_ashr_i32 s2, s7, 3
	s_cbranch_execz .LBB0_994
	s_branch .LBB0_995
